# attention: V transpose-reads (and half-B next-tile loads) hoisted above the permlane swap tail, on top of K swizzle + counted PV waits
# baseline (speedup 1.0000x reference)
; #define SBAR() __builtin_amdgcn_sched_barrier(0)
; #define QKT(P0, P1, KP) do { if constexpr (PRE) qkt<ND0>(P0, P1, KP, qr, r32, hi, negm); else qkt<ND0>(P0, P1, KP, qr, r32, hi); } while (0)
; #define PSM(P0, P1, MN, AL, FIRST) do { if constexpr (PRE) partialSM2(P0, P1, m_reg, negm, AL, thr2, FIRST); else partialSM(P0, P1, m_reg, MN, AL, C, thr_raw); } while (0)
; DEVFI void finishSM(f32x16& p0, f32x16& p1, float alpha, float& l_reg, bf16x8& pa0, bf16x8& pa1, bf16x8& pa2, bf16x8& pa3) {
; #pragma unroll
;     for (int r = 0; r < 16; ++r) p1[r] = __builtin_amdgcn_exp2f(p1[r]);
;     float ps = 0;
; #pragma unroll
;     for (int r = 0; r < 16; ++r) ps += p0[r];
; #pragma unroll
;     for (int r = 0; r < 16; ++r) ps += p1[r];
;     { auto rr = __builtin_amdgcn_permlane32_swap(__float_as_uint(ps), __float_as_uint(ps), false, false);
;       ps = __uint_as_float(rr[0]) + __uint_as_float(rr[1]); }
;     l_reg = l_reg * alpha + ps;
;     ...
;     PK4(p0, 0, pa0); PK4(p0, 8, pa1); PK4(p1, 0, pa2); PK4(p1, 8, pa3);
; template <int DQK, int DV, bool PRE = false>
; DEVFI void attn_unit(const bf16_t* __restrict__ Qb, int ldq, const bf16_t* __restrict__ Kh, int ldk, const bf16_t* __restrict__ Vh, int ldv,
;                      bf16_t* __restrict__ Ob, int ldo, int seq, float scale, char* lds) {
;     ...
;         SBAR(); QKT(pB0, pB1, K_lds + SHM_K);
;         finishSM(pA0, pA1, alA, l_reg, pa0, pa1, pa2, pa3); SBAR();
;         SLOAD(1, (j + 2) * KVBLK); SBAR();
;         pv_all<NCB>(o, vb0, pa0, pa1, pa2, pa3); PSM(pB0, pB1, mnB, alB, false);
.LBB0_1151:
	ds_read_b128 v[0:3], v177 offset:32768
	ds_read_b128 v[4:7], v177 offset:40960
	v_add_f32_e32 v8, 0, v203
	v_add_f32_e32 v8, v205, v8
	v_add_f32_e32 v8, v189, v8
	s_waitcnt lgkmcnt(1)
	v_mfma_f32_32x32x16_bf16 v[94:109], v[0:3], v[130:133], v[46:61]
	v_add_f32_e32 v8, v204, v8
	v_add_f32_e32 v8, v187, v8
	v_add_f32_e32 v8, v202, v8
	v_add_f32_e32 v8, v186, v8
	v_add_f32_e32 v8, v188, v8
	v_add_f32_e32 v8, v183, v8
	v_add_f32_e32 v8, v185, v8
	s_waitcnt lgkmcnt(0)
	v_mfma_f32_32x32x16_bf16 v[78:93], v[4:7], v[130:133], v[46:61]
	ds_read_b128 v[0:3], v178 offset:32768
	ds_read_b128 v[4:7], v178 offset:40960
	v_add_f32_e32 v8, v163, v8
	v_add_f32_e32 v8, v184, v8
	v_add_f32_e32 v8, v161, v8
	v_add_f32_e32 v8, v182, v8
	v_add_f32_e32 v8, v160, v8
	v_add_f32_e32 v8, v162, v8
	s_waitcnt lgkmcnt(1)
	v_mfma_f32_32x32x16_bf16 v[94:109], v[0:3], v[126:129], v[94:109]
	v_exp_f32_e32 v70, v70
	v_exp_f32_e32 v71, v71
	v_exp_f32_e32 v72, v72
	v_exp_f32_e32 v73, v73
	v_exp_f32_e32 v74, v74
	v_exp_f32_e32 v75, v75
	v_exp_f32_e32 v76, v76
	s_waitcnt lgkmcnt(0)
	v_mfma_f32_32x32x16_bf16 v[78:93], v[4:7], v[126:129], v[78:93]
	ds_read_b128 v[0:3], v176 offset:32768
	ds_read_b128 v[4:7], v176 offset:40960
	v_exp_f32_e32 v77, v77
	s_waitcnt lgkmcnt(1)
	v_mfma_f32_32x32x16_bf16 v[94:109], v[0:3], v[122:125], v[94:109]
	s_waitcnt lgkmcnt(0)
	v_mfma_f32_32x32x16_bf16 v[78:93], v[4:7], v[122:125], v[78:93]
	ds_read_b128 v[0:3], v175 offset:32768
	ds_read_b128 v[4:7], v175 offset:40960
	s_waitcnt lgkmcnt(1)
	v_mfma_f32_32x32x16_bf16 v[94:109], v[0:3], v[118:121], v[94:109]
	s_waitcnt lgkmcnt(0)
	v_mfma_f32_32x32x16_bf16 v[78:93], v[4:7], v[118:121], v[78:93]
	ds_read_b128 v[0:3], v174 offset:32768
	ds_read_b128 v[4:7], v174 offset:40960
	s_waitcnt lgkmcnt(1)
	v_mfma_f32_32x32x16_bf16 v[94:109], v[0:3], v[114:117], v[94:109]
	s_waitcnt lgkmcnt(0)
	v_mfma_f32_32x32x16_bf16 v[78:93], v[4:7], v[114:117], v[78:93]
	ds_read_b128 v[0:3], v172 offset:32768
	ds_read_b128 v[4:7], v172 offset:40960
	s_waitcnt lgkmcnt(1)
	v_mfma_f32_32x32x16_bf16 v[94:109], v[0:3], v[110:113], v[94:109]
	v_exp_f32_e32 v0, v62
	v_exp_f32_e32 v1, v63
	v_exp_f32_e32 v2, v64
	v_exp_f32_e32 v3, v65
	v_add_f32_e32 v8, v0, v8
	v_add_f32_e32 v8, v1, v8
	v_add_f32_e32 v8, v2, v8
	s_waitcnt lgkmcnt(0)
	v_mfma_f32_32x32x16_bf16 v[78:93], v[4:7], v[110:113], v[78:93]
	v_exp_f32_e32 v4, v66
	v_exp_f32_e32 v5, v67
	v_exp_f32_e32 v6, v68
	v_exp_f32_e32 v7, v69
	v_add_f32_e32 v8, v3, v8
	v_add_f32_e32 v8, v4, v8
	v_add_f32_e32 v8, v5, v8
	v_add_f32_e32 v8, v6, v8
	v_add_f32_e32 v8, v7, v8
	v_add_f32_e32 v8, v70, v8
	v_add_f32_e32 v8, v71, v8
	v_add_f32_e32 v8, v72, v8
	v_add_f32_e32 v8, v73, v8
	v_add_f32_e32 v8, v74, v8
	v_add_f32_e32 v8, v75, v8
	v_add_f32_e32 v8, v76, v8
	v_add_f32_e32 v13, v77, v8
	v_mov_b32_e32 v180, v13
	v_cvt_pk_bf16_f32 v8, v203, v205
	v_cvt_pk_bf16_f32 v9, v189, v204
	v_cvt_pk_bf16_f32 v10, v187, v202
	v_cvt_pk_bf16_f32 v11, v186, v188
	v_cvt_pk_bf16_f32 v62, v183, v185
	v_cvt_pk_bf16_f32 v63, v163, v184
	v_cvt_pk_bf16_f32 v64, v161, v182
	v_cvt_pk_bf16_f32 v65, v160, v162
	v_cvt_pk_bf16_f32 v66, v0, v1
	v_cvt_pk_bf16_f32 v67, v2, v3
	v_cvt_pk_bf16_f32 v68, v4, v5
	v_cvt_pk_bf16_f32 v69, v6, v7
	v_cvt_pk_bf16_f32 v70, v70, v71
	v_cvt_pk_bf16_f32 v71, v72, v73
	v_cvt_pk_bf16_f32 v72, v74, v75
	v_cvt_pk_bf16_f32 v73, v76, v77
	ds_read_b64_tr_b16 v[74:75], v171 offset:0
	ds_read_b64_tr_b16 v[76:77], v171 offset:0x400
	ds_read_b64_tr_b16 v[182:183], v171 offset:0x800
	ds_read_b64_tr_b16 v[184:185], v171 offset:0xc00
	ds_read_b64_tr_b16 v[186:187], v171 offset:0x1000
	ds_read_b64_tr_b16 v[188:189], v171 offset:0x1400
	ds_read_b64_tr_b16 v[202:203], v171 offset:0x1800
	ds_read_b64_tr_b16 v[204:205], v171 offset:0x1c00
	s_nop 1
	v_permlane32_swap_b32_e32 v13, v180
	v_permlane32_swap_b32_e32 v8, v10
	v_permlane32_swap_b32_e32 v9, v11
	v_permlane32_swap_b32_e32 v62, v64
	v_permlane32_swap_b32_e32 v63, v65
	v_permlane32_swap_b32_e32 v66, v68
	v_permlane32_swap_b32_e32 v67, v69
	v_permlane32_swap_b32_e32 v70, v72
	v_permlane32_swap_b32_e32 v71, v73
	v_lshl_add_u64 v[160:161], s[10:11], 0, v[158:159]
	v_add_co_u32_e32 v0, vcc, 0x2cc48000, v160
	s_nop 1
	v_addc_co_u32_e32 v1, vcc, 0, v161, vcc
	global_load_dwordx4 v[0:3], v[0:1], off
	s_and_saveexec_b64 s[0:1], s[42:43]
	s_cbranch_execz .LBB0_1153
	v_lshl_add_u64 v[4:5], s[10:11], 0, v[154:155]
	v_add_co_u32_e32 v4, vcc, 0x2cc48000, v4
	s_nop 1
	v_addc_co_u32_e32 v5, vcc, 0, v5, vcc
	global_load_dwordx4 v[138:141], v[4:5], off
; #define SBAR() __builtin_amdgcn_sched_barrier(0)
; template <int OFF> DEVFI s16x4 tr_read(int vb) { s16x4 r; asm volatile("ds_read_b64_tr_b16 %0, %1 offset:%2" : "=&v"(r) : "v"(vb), "i"(OFF) : "memory"); return r; }
; DEVFI void partialSM2(f32x16& p0, f32x16& p1, float& mhat, f32x16& negm, float& alpha, const float thr2, const bool first) {
;     float pmax = p0[0];
; #pragma unroll
;     for (int r = 1; r < 16; ++r) pmax = fmaxf(pmax, p0[r]);
; #pragma unroll
;     for (int r = 0; r < 16; ++r) pmax = fmaxf(pmax, p1[r]);
;     { auto rr = __builtin_amdgcn_permlane32_swap(__float_as_uint(pmax), __float_as_uint(pmax), false, false);
;       pmax = fmaxf(__uint_as_float(rr[0]), __uint_as_float(rr[1])); }
;     alpha = 1.f;
;     if (first || !__all(pmax <= thr2)) {
;         const float dl = first ? pmax : fmaxf(pmax, 0.f);
;         mhat += dl; alpha = first ? 1.f : __builtin_amdgcn_exp2f(-dl);
; #pragma unroll
;         for (int r = 0; r < 16; ++r) { p0[r] -= dl; p1[r] -= dl; }
; #pragma unroll
;         for (int r = 0; r < 16; ++r) negm[r] = -mhat;
;         asm volatile("" : "+v"(negm));
;     }
; template <int NCB, int D0> DEVFI void pv_one(f32x16& od, int vb, bf16x8 pa0, bf16x8 pa1, bf16x8 pa2, bf16x8 pa3) {
;     ...
;     const s16x4 l0 = tr_read<VOFF(0, 0)>(vb), h0 = tr_read<VOFF(0, 1)>(vb), l1 = tr_read<VOFF(1, 0)>(vb), h1 = tr_read<VOFF(1, 1)>(vb);
;     const s16x4 l2 = tr_read<VOFF(2, 0)>(vb), h2 = tr_read<VOFF(2, 1)>(vb), l3 = tr_read<VOFF(3, 0)>(vb), h3 = tr_read<VOFF(3, 1)>(vb);
;     ...
;     asm volatile("s_waitcnt lgkmcnt(0)" ::: "memory"); SBAR();
;     ...
;     od = __builtin_amdgcn_mfma_f32_32x32x16_bf16(pa0, PK(l0, h0), od, 0, 0, 0);
;     od = __builtin_amdgcn_mfma_f32_32x32x16_bf16(pa1, PK(l1, h1), od, 0, 0, 0);
;     od = __builtin_amdgcn_mfma_f32_32x32x16_bf16(pa2, PK(l2, h2), od, 0, 0, 0);
;     od = __builtin_amdgcn_mfma_f32_32x32x16_bf16(pa3, PK(l3, h3), od, 0, 0, 0);
;     ...
; }
.LBB0_1153:
	s_or_b64 exec, exec, s[0:1]
	v_lshl_add_u64 v[162:163], s[10:11], 0, v[156:157]
	v_add_co_u32_e32 v4, vcc, 0x2fc30000, v162
	s_nop 1
	v_addc_co_u32_e32 v5, vcc, 0, v163, vcc
	global_load_dwordx4 v[4:7], v[4:5], off
	s_waitcnt lgkmcnt(6)
	s_nop 0
	v_mfma_f32_32x32x16_bf16 v[30:45], v[8:11], v[74:77], v[30:45]
	ds_read_b64_tr_b16 v[74:75], v171 offset:0x200
	ds_read_b64_tr_b16 v[76:77], v171 offset:0x600
	s_waitcnt lgkmcnt(6)
	v_mfma_f32_32x32x16_bf16 v[30:45], v[62:65], v[182:185], v[30:45]
	ds_read_b64_tr_b16 v[182:183], v171 offset:0xa00
	ds_read_b64_tr_b16 v[184:185], v171 offset:0xe00
	s_waitcnt lgkmcnt(6)
	v_mfma_f32_32x32x16_bf16 v[30:45], v[66:69], v[186:189], v[30:45]
	ds_read_b64_tr_b16 v[186:187], v171 offset:0x1200
	ds_read_b64_tr_b16 v[188:189], v171 offset:0x1600
	s_waitcnt lgkmcnt(6)
	v_mfma_f32_32x32x16_bf16 v[30:45], v[70:73], v[202:205], v[30:45]
	ds_read_b64_tr_b16 v[202:203], v171 offset:0x1a00
	ds_read_b64_tr_b16 v[204:205], v171 offset:0x1e00
	s_waitcnt lgkmcnt(6)
	v_mfma_f32_32x32x16_bf16 v[14:29], v[8:11], v[74:77], v[14:29]
	v_max_f32_e32 v8, v95, v95
	v_max_f32_e32 v9, v94, v94
	v_max_f32_e32 v8, v9, v8
	v_max3_f32 v8, v8, v96, v97
	v_max3_f32 v8, v8, v98, v99
	v_max3_f32 v8, v8, v100, v101
	v_max3_f32 v8, v8, v102, v103
	s_waitcnt lgkmcnt(4)
	v_mfma_f32_32x32x16_bf16 v[14:29], v[62:65], v[182:185], v[14:29]
	v_max3_f32 v8, v8, v104, v105
	v_max3_f32 v8, v8, v106, v107
	v_max3_f32 v8, v8, v108, v109
	v_max3_f32 v8, v8, v78, v79
	v_max3_f32 v8, v8, v80, v81
	v_max3_f32 v8, v8, v82, v83
	v_max3_f32 v8, v8, v84, v85
	s_waitcnt lgkmcnt(2)
	v_mfma_f32_32x32x16_bf16 v[14:29], v[66:69], v[186:189], v[14:29]
	v_max3_f32 v8, v8, v86, v87
	v_max3_f32 v8, v8, v88, v89
	v_max3_f32 v8, v8, v90, v91
	v_max3_f32 v8, v8, v92, v93
	v_mov_b32_e32 v9, v8
	s_nop 1
	v_permlane32_swap_b32_e32 v8, v9
	s_waitcnt lgkmcnt(0)
	v_mfma_f32_32x32x16_bf16 v[14:29], v[70:73], v[202:205], v[14:29]
	v_max_f32_e32 v9, v9, v9
	v_max_f32_e32 v8, v8, v8
	v_max_f32_e32 v8, v8, v9
	v_cmp_ge_f32_e32 vcc, s33, v8
	s_cmp_eq_u64 vcc, exec
	v_mov_b32_e32 v181, 1.0
	s_cbranch_scc1 .LBB0_1155
	v_max_f32_e32 v8, v8, v8
	v_max_f32_e32 v8, 0, v8
	v_exp_f32_e64 v181, -v8
	v_add_f32_e32 v168, v168, v8
	v_xor_b32_e32 v46, 0x80000000, v168
	v_pk_add_f32 v[94:95], v[94:95], v[8:9] op_sel_hi:[1,0] neg_lo:[0,1] neg_hi:[0,1]
	v_pk_add_f32 v[96:97], v[96:97], v[8:9] op_sel_hi:[1,0] neg_lo:[0,1] neg_hi:[0,1]
	v_pk_add_f32 v[98:99], v[98:99], v[8:9] op_sel_hi:[1,0] neg_lo:[0,1] neg_hi:[0,1]
	v_pk_add_f32 v[100:101], v[100:101], v[8:9] op_sel_hi:[1,0] neg_lo:[0,1] neg_hi:[0,1]
	v_pk_add_f32 v[102:103], v[102:103], v[8:9] op_sel_hi:[1,0] neg_lo:[0,1] neg_hi:[0,1]
	v_pk_add_f32 v[104:105], v[104:105], v[8:9] op_sel_hi:[1,0] neg_lo:[0,1] neg_hi:[0,1]
	v_pk_add_f32 v[106:107], v[106:107], v[8:9] op_sel_hi:[1,0] neg_lo:[0,1] neg_hi:[0,1]
	v_pk_add_f32 v[108:109], v[108:109], v[8:9] op_sel_hi:[1,0] neg_lo:[0,1] neg_hi:[0,1]
	v_sub_f32_e32 v93, v93, v8
	v_sub_f32_e32 v92, v92, v8
	v_sub_f32_e32 v91, v91, v8
	v_sub_f32_e32 v90, v90, v8
	v_sub_f32_e32 v89, v89, v8
	v_sub_f32_e32 v88, v88, v8
	v_sub_f32_e32 v87, v87, v8
	v_sub_f32_e32 v86, v86, v8
	v_sub_f32_e32 v85, v85, v8
	v_sub_f32_e32 v84, v84, v8
	v_sub_f32_e32 v83, v83, v8
	v_sub_f32_e32 v82, v82, v8
	v_sub_f32_e32 v81, v81, v8
	v_sub_f32_e32 v80, v80, v8
	v_sub_f32_e32 v79, v79, v8
	v_sub_f32_e32 v78, v78, v8
	v_mov_b32_e32 v47, v46
	v_mov_b32_e32 v48, v46
	v_mov_b32_e32 v49, v46
	v_mov_b32_e32 v50, v46
	v_mov_b32_e32 v51, v46
	v_mov_b32_e32 v52, v46
	v_mov_b32_e32 v53, v46
	v_mov_b32_e32 v54, v46
	v_mov_b32_e32 v55, v46
	v_mov_b32_e32 v56, v46
	v_mov_b32_e32 v57, v46
	v_mov_b32_e32 v58, v46
	v_mov_b32_e32 v59, v46
	v_mov_b32_e32 v60, v46
	v_mov_b32_e32 v61, v46

; #define SBAR() __builtin_amdgcn_sched_barrier(0)
; #define QKT(P0, P1, KP) do { if constexpr (PRE) qkt<ND0>(P0, P1, KP, qr, r32, hi, negm); else qkt<ND0>(P0, P1, KP, qr, r32, hi); } while (0)
; DEVFI void finishSM(f32x16& p0, f32x16& p1, float alpha, float& l_reg, bf16x8& pa0, bf16x8& pa1, bf16x8& pa2, bf16x8& pa3) {
; #pragma unroll
;     for (int r = 0; r < 16; ++r) p1[r] = __builtin_amdgcn_exp2f(p1[r]);
;     float ps = 0;
; #pragma unroll
;     for (int r = 0; r < 16; ++r) ps += p0[r];
; #pragma unroll
;     for (int r = 0; r < 16; ++r) ps += p1[r];
;     { auto rr = __builtin_amdgcn_permlane32_swap(__float_as_uint(ps), __float_as_uint(ps), false, false);
;       ps = __uint_as_float(rr[0]) + __uint_as_float(rr[1]); }
;     l_reg = l_reg * alpha + ps;
;     ...
;     PK4(p0, 0, pa0); PK4(p0, 8, pa1); PK4(p1, 0, pa2); PK4(p1, 8, pa3);
; template <int DQK, int DV, bool PRE = false>
; DEVFI void attn_unit(const bf16_t* __restrict__ Qb, int ldq, const bf16_t* __restrict__ Kh, int ldk, const bf16_t* __restrict__ Vh, int ldv,
;                      bf16_t* __restrict__ Ob, int ldo, int seq, float scale, char* lds) {
;     ...
;         SBAR(); QKT(pA0, pA1, K_lds);
;         finishSM(pB0, pB1, alB, l_reg, pa0, pa1, pa2, pa3); SBAR();
;         if (j + 3 < NT) SLOAD(0, (j + 3) * KVBLK); SBAR();
.LBB0_1161:
	v_exp_f32_e32 v8, v94
	v_exp_f32_e32 v9, v96
	v_exp_f32_e32 v10, v98
	v_exp_f32_e32 v11, v100
	v_exp_f32_e32 v205, v95
	v_exp_f32_e32 v204, v97
	v_exp_f32_e32 v203, v99
	v_exp_f32_e32 v202, v101
	v_exp_f32_e32 v187, v102
	v_exp_f32_e32 v189, v103
	v_exp_f32_e32 v185, v104
	v_exp_f32_e32 v188, v105
	v_exp_f32_e32 v183, v106
	v_exp_f32_e32 v186, v107
	v_exp_f32_e32 v182, v108
	v_exp_f32_e32 v184, v109
	s_waitcnt lgkmcnt(0)
	s_barrier
	ds_read_b128 v[62:65], v177 offset:16384
	ds_read_b128 v[206:209], v177 offset:24576
	v_exp_f32_e32 v190, v78
	v_add_f32_e32 v78, 0, v8
	v_add_f32_e32 v78, v205, v78
	s_waitcnt lgkmcnt(1)
	v_mfma_f32_32x32x16_bf16 v[94:109], v[62:65], v[130:133], v[46:61]
	v_add_f32_e32 v78, v9, v78
	v_add_f32_e32 v78, v204, v78
	v_add_f32_e32 v78, v10, v78
	v_add_f32_e32 v78, v203, v78
	v_add_f32_e32 v78, v11, v78
	v_add_f32_e32 v78, v202, v78
	v_add_f32_e32 v78, v187, v78
	s_waitcnt lgkmcnt(0)
	v_mfma_f32_32x32x16_bf16 v[62:77], v[206:209], v[130:133], v[46:61]
	ds_read_b128 v[206:209], v178 offset:16384
	ds_read_b128 v[210:213], v178 offset:24576
	v_add_f32_e32 v78, v189, v78
	v_add_f32_e32 v78, v185, v78
	v_add_f32_e32 v78, v188, v78
	v_add_f32_e32 v78, v183, v78
	v_exp_f32_e32 v191, v79
	v_add_f32_e32 v78, v186, v78
	s_waitcnt lgkmcnt(1)
	v_mfma_f32_32x32x16_bf16 v[94:109], v[206:209], v[126:129], v[94:109]
	v_add_f32_e32 v78, v182, v78
	v_add_f32_e32 v78, v184, v78
	v_add_f32_e32 v78, v190, v78
	v_add_f32_e32 v78, v191, v78
	v_exp_f32_e32 v85, v85
	v_exp_f32_e32 v86, v86
	v_exp_f32_e32 v87, v87
	s_waitcnt lgkmcnt(0)
	v_mfma_f32_32x32x16_bf16 v[62:77], v[210:213], v[126:129], v[62:77]
	ds_read_b128 v[206:209], v176 offset:16384
	ds_read_b128 v[210:213], v176 offset:24576
	v_exp_f32_e32 v88, v88
	v_exp_f32_e32 v89, v89
	v_exp_f32_e32 v92, v92
	v_exp_f32_e32 v93, v93
	s_waitcnt lgkmcnt(1)
	v_mfma_f32_32x32x16_bf16 v[94:109], v[206:209], v[122:125], v[94:109]
	s_waitcnt lgkmcnt(0)
	v_mfma_f32_32x32x16_bf16 v[62:77], v[210:213], v[122:125], v[62:77]
	ds_read_b128 v[206:209], v175 offset:16384
	ds_read_b128 v[210:213], v175 offset:24576
	s_waitcnt lgkmcnt(1)
	v_mfma_f32_32x32x16_bf16 v[94:109], v[206:209], v[118:121], v[94:109]
	s_waitcnt lgkmcnt(0)
	v_mfma_f32_32x32x16_bf16 v[62:77], v[210:213], v[118:121], v[62:77]
	ds_read_b128 v[206:209], v174 offset:16384
	ds_read_b128 v[210:213], v174 offset:24576
	s_waitcnt lgkmcnt(1)
	v_mfma_f32_32x32x16_bf16 v[94:109], v[206:209], v[114:117], v[94:109]
	s_waitcnt lgkmcnt(0)
	v_mfma_f32_32x32x16_bf16 v[62:77], v[210:213], v[114:117], v[62:77]
	ds_read_b128 v[206:209], v172 offset:16384
	ds_read_b128 v[210:213], v172 offset:24576
	v_cvt_pk_bf16_f32 v8, v8, v205
	v_cvt_pk_bf16_f32 v9, v9, v204
	v_cvt_pk_bf16_f32 v10, v10, v203
	v_cvt_pk_bf16_f32 v11, v11, v202
	s_nop 0
	v_permlane32_swap_b32_e32 v8, v10
	s_waitcnt lgkmcnt(1)
	v_mfma_f32_32x32x16_bf16 v[94:109], v[206:209], v[110:113], v[94:109]
	v_exp_f32_e32 v206, v80
	v_exp_f32_e32 v207, v81
	v_exp_f32_e32 v208, v82
	v_exp_f32_e32 v209, v83
	v_add_f32_e32 v78, v206, v78
	v_add_f32_e32 v78, v207, v78
	v_add_f32_e32 v78, v208, v78
	s_waitcnt lgkmcnt(0)
	v_mfma_f32_32x32x16_bf16 v[62:77], v[210:213], v[110:113], v[62:77]
	v_exp_f32_e32 v210, v84
	v_add_f32_e32 v78, v209, v78
	v_exp_f32_e32 v211, v90
	v_exp_f32_e32 v212, v91
	v_add_f32_e32 v78, v210, v78
	v_add_f32_e32 v78, v85, v78
	v_add_f32_e32 v78, v86, v78
	v_add_f32_e32 v78, v87, v78
	v_add_f32_e32 v78, v88, v78
	v_add_f32_e32 v78, v89, v78
	v_add_f32_e32 v78, v211, v78
	v_add_f32_e32 v78, v212, v78
	v_add_f32_e32 v78, v92, v78
	v_add_f32_e32 v90, v93, v78
	v_mov_b32_e32 v91, v90
	v_cvt_pk_bf16_f32 v78, v187, v189
	v_cvt_pk_bf16_f32 v79, v185, v188
	v_cvt_pk_bf16_f32 v80, v183, v186
	v_cvt_pk_bf16_f32 v81, v182, v184
	v_cvt_pk_bf16_f32 v82, v190, v191
	v_cvt_pk_bf16_f32 v83, v206, v207
	v_cvt_pk_bf16_f32 v84, v208, v209
	v_cvt_pk_bf16_f32 v85, v210, v85
	v_cvt_pk_bf16_f32 v86, v86, v87
	v_cvt_pk_bf16_f32 v87, v88, v89
	v_cvt_pk_bf16_f32 v88, v211, v212
	v_cvt_pk_bf16_f32 v89, v92, v93
	s_cmp_ge_u32 s18, s59
	s_cselect_b64 s[0:1], -1, 0
	s_and_b64 vcc, exec, s[0:1]
	s_cbranch_vccnz .LBB0_1165
	v_add_co_u32_e32 v92, vcc, 0x2cc60000, v160
	s_nop 1
	v_addc_co_u32_e32 v93, vcc, 0, v161, vcc
	global_load_dwordx4 v[142:145], v[92:93], off
	s_and_saveexec_b64 s[16:17], s[42:43]
	s_cbranch_execz .LBB0_1164
	v_lshl_add_u64 v[92:93], s[10:11], 0, v[154:155]
	v_add_co_u32_e32 v92, vcc, 0x2cc60000, v92
	s_nop 1
	v_addc_co_u32_e32 v93, vcc, 0, v93, vcc
	global_load_dwordx4 v[134:137], v[92:93], off

; #define SBAR() __builtin_amdgcn_sched_barrier(0)
; template <int OFF> DEVFI s16x4 tr_read(int vb) { s16x4 r; asm volatile("ds_read_b64_tr_b16 %0, %1 offset:%2" : "=&v"(r) : "v"(vb), "i"(OFF) : "memory"); return r; }
; DEVFI void partialSM2(f32x16& p0, f32x16& p1, float& mhat, f32x16& negm, float& alpha, const float thr2, const bool first) {
;     float pmax = p0[0];
; #pragma unroll
;     for (int r = 1; r < 16; ++r) pmax = fmaxf(pmax, p0[r]);
; #pragma unroll
;     for (int r = 0; r < 16; ++r) pmax = fmaxf(pmax, p1[r]);
;     { auto rr = __builtin_amdgcn_permlane32_swap(__float_as_uint(pmax), __float_as_uint(pmax), false, false);
;       pmax = fmaxf(__uint_as_float(rr[0]), __uint_as_float(rr[1])); }
;     alpha = 1.f;
;     if (first || !__all(pmax <= thr2)) {
;         const float dl = first ? pmax : fmaxf(pmax, 0.f);
;         mhat += dl; alpha = first ? 1.f : __builtin_amdgcn_exp2f(-dl);
; #pragma unroll
;         for (int r = 0; r < 16; ++r) { p0[r] -= dl; p1[r] -= dl; }
; #pragma unroll
;         for (int r = 0; r < 16; ++r) negm[r] = -mhat;
;         asm volatile("" : "+v"(negm));
;     }
; template <int NCB, int D0> DEVFI void pv_one(f32x16& od, int vb, bf16x8 pa0, bf16x8 pa1, bf16x8 pa2, bf16x8 pa3) {
;     ...
;     const s16x4 l0 = tr_read<VOFF(0, 0)>(vb), h0 = tr_read<VOFF(0, 1)>(vb), l1 = tr_read<VOFF(1, 0)>(vb), h1 = tr_read<VOFF(1, 1)>(vb);
;     const s16x4 l2 = tr_read<VOFF(2, 0)>(vb), h2 = tr_read<VOFF(2, 1)>(vb), l3 = tr_read<VOFF(3, 0)>(vb), h3 = tr_read<VOFF(3, 1)>(vb);
;     ...
;     asm volatile("s_waitcnt lgkmcnt(0)" ::: "memory"); SBAR();
;     ...
;     od = __builtin_amdgcn_mfma_f32_32x32x16_bf16(pa0, PK(l0, h0), od, 0, 0, 0);
;     od = __builtin_amdgcn_mfma_f32_32x32x16_bf16(pa1, PK(l1, h1), od, 0, 0, 0);
;     od = __builtin_amdgcn_mfma_f32_32x32x16_bf16(pa2, PK(l2, h2), od, 0, 0, 0);
;     od = __builtin_amdgcn_mfma_f32_32x32x16_bf16(pa3, PK(l3, h3), od, 0, 0, 0);
;     ...
; }
.LBB0_1165:
	ds_read_b64_tr_b16 v[160:161], v167 offset:0
	ds_read_b64_tr_b16 v[162:163], v167 offset:0x400
	ds_read_b64_tr_b16 v[182:183], v167 offset:0x800
	ds_read_b64_tr_b16 v[184:185], v167 offset:0xc00
	ds_read_b64_tr_b16 v[186:187], v167 offset:0x1000
	ds_read_b64_tr_b16 v[188:189], v167 offset:0x1400
	ds_read_b64_tr_b16 v[202:203], v167 offset:0x1800
	ds_read_b64_tr_b16 v[204:205], v167 offset:0x1c00
	s_nop 1
	v_permlane32_swap_b32_e32 v90, v91
	v_permlane32_swap_b32_e32 v9, v11
	v_permlane32_swap_b32_e32 v78, v80
	v_permlane32_swap_b32_e32 v79, v81
	v_permlane32_swap_b32_e32 v82, v84
	v_permlane32_swap_b32_e32 v83, v85
	v_permlane32_swap_b32_e32 v86, v88
	v_permlane32_swap_b32_e32 v87, v89
	s_waitcnt lgkmcnt(6)
	s_nop 0
	v_mfma_f32_32x32x16_bf16 v[30:45], v[8:11], v[160:163], v[30:45]
	ds_read_b64_tr_b16 v[160:161], v167 offset:0x200
	ds_read_b64_tr_b16 v[162:163], v167 offset:0x600
	s_waitcnt lgkmcnt(6)
	v_mfma_f32_32x32x16_bf16 v[30:45], v[78:81], v[182:185], v[30:45]
	ds_read_b64_tr_b16 v[182:183], v167 offset:0xa00
	ds_read_b64_tr_b16 v[184:185], v167 offset:0xe00
	s_waitcnt lgkmcnt(6)
	v_mfma_f32_32x32x16_bf16 v[30:45], v[82:85], v[186:189], v[30:45]
	ds_read_b64_tr_b16 v[186:187], v167 offset:0x1200
	ds_read_b64_tr_b16 v[188:189], v167 offset:0x1600
	s_waitcnt lgkmcnt(6)
	v_mfma_f32_32x32x16_bf16 v[30:45], v[86:89], v[202:205], v[30:45]
	ds_read_b64_tr_b16 v[202:203], v167 offset:0x1a00
	ds_read_b64_tr_b16 v[204:205], v167 offset:0x1e00
	s_waitcnt lgkmcnt(6)
	v_mfma_f32_32x32x16_bf16 v[14:29], v[8:11], v[160:163], v[14:29]
	v_max_f32_e32 v8, v95, v95
	v_max_f32_e32 v9, v94, v94
	v_max_f32_e32 v8, v9, v8
	v_max3_f32 v8, v8, v96, v97
	v_max3_f32 v8, v8, v98, v99
	v_max3_f32 v8, v8, v100, v101
	v_max3_f32 v8, v8, v102, v103
	s_waitcnt lgkmcnt(4)
	v_mfma_f32_32x32x16_bf16 v[14:29], v[78:81], v[182:185], v[14:29]
	v_max3_f32 v8, v8, v104, v105
	v_max3_f32 v8, v8, v106, v107
	v_max3_f32 v8, v8, v108, v109
	v_max3_f32 v8, v8, v62, v63
	v_max3_f32 v8, v8, v64, v65
	v_max3_f32 v8, v8, v66, v67
	v_max3_f32 v8, v8, v68, v69
	s_waitcnt lgkmcnt(2)
	v_mfma_f32_32x32x16_bf16 v[14:29], v[82:85], v[186:189], v[14:29]
	v_max3_f32 v8, v8, v70, v71
	v_max3_f32 v8, v8, v72, v73
	v_max3_f32 v8, v8, v74, v75
	v_max3_f32 v8, v8, v76, v77
	v_mov_b32_e32 v9, v8
	s_nop 1
	v_permlane32_swap_b32_e32 v8, v9
	s_waitcnt lgkmcnt(0)
	v_mfma_f32_32x32x16_bf16 v[14:29], v[86:89], v[202:205], v[14:29]
	v_max_f32_e32 v9, v9, v9
	v_max_f32_e32 v8, v8, v8
	v_max_f32_e32 v9, v8, v9
	v_cmp_ge_f32_e32 vcc, s33, v9
	s_cmp_eq_u64 vcc, exec
	v_mov_b32_e32 v8, 1.0
	s_cbranch_scc1 .LBB0_1167
	v_max_f32_e32 v8, v9, v9
	v_max_f32_e32 v10, 0, v8
	v_exp_f32_e64 v8, -v10
	v_add_f32_e32 v168, v168, v10
	v_xor_b32_e32 v46, 0x80000000, v168
	v_pk_add_f32 v[94:95], v[94:95], v[10:11] op_sel_hi:[1,0] neg_lo:[0,1] neg_hi:[0,1]
	v_pk_add_f32 v[96:97], v[96:97], v[10:11] op_sel_hi:[1,0] neg_lo:[0,1] neg_hi:[0,1]
	v_pk_add_f32 v[98:99], v[98:99], v[10:11] op_sel_hi:[1,0] neg_lo:[0,1] neg_hi:[0,1]
	v_pk_add_f32 v[100:101], v[100:101], v[10:11] op_sel_hi:[1,0] neg_lo:[0,1] neg_hi:[0,1]
	v_pk_add_f32 v[102:103], v[102:103], v[10:11] op_sel_hi:[1,0] neg_lo:[0,1] neg_hi:[0,1]
	v_pk_add_f32 v[104:105], v[104:105], v[10:11] op_sel_hi:[1,0] neg_lo:[0,1] neg_hi:[0,1]
	v_pk_add_f32 v[106:107], v[106:107], v[10:11] op_sel_hi:[1,0] neg_lo:[0,1] neg_hi:[0,1]
	v_pk_add_f32 v[108:109], v[108:109], v[10:11] op_sel_hi:[1,0] neg_lo:[0,1] neg_hi:[0,1]
	v_sub_f32_e32 v77, v77, v10
	v_sub_f32_e32 v76, v76, v10
	v_sub_f32_e32 v75, v75, v10
	v_sub_f32_e32 v74, v74, v10
	v_sub_f32_e32 v73, v73, v10
	v_sub_f32_e32 v72, v72, v10
	v_sub_f32_e32 v71, v71, v10
	v_sub_f32_e32 v70, v70, v10
	v_sub_f32_e32 v69, v69, v10
	v_sub_f32_e32 v68, v68, v10
	v_sub_f32_e32 v67, v67, v10
	v_sub_f32_e32 v66, v66, v10
	v_sub_f32_e32 v65, v65, v10
	v_sub_f32_e32 v64, v64, v10
	v_sub_f32_e32 v63, v63, v10
	v_sub_f32_e32 v62, v62, v10
	v_mov_b32_e32 v47, v46
	v_mov_b32_e32 v48, v46
	v_mov_b32_e32 v49, v46
	v_mov_b32_e32 v50, v46
	v_mov_b32_e32 v51, v46
	v_mov_b32_e32 v52, v46
	v_mov_b32_e32 v53, v46
	v_mov_b32_e32 v54, v46
	v_mov_b32_e32 v55, v46
	v_mov_b32_e32 v56, v46
	v_mov_b32_e32 v57, v46
	v_mov_b32_e32 v58, v46
	v_mov_b32_e32 v59, v46
	v_mov_b32_e32 v60, v46
	v_mov_b32_e32 v61, v46
